# attention stagger of waves 4-7 lengthened to s_sleep 24 (about half a j-iteration), otherwise v132
# baseline (speedup 1.0000x reference)
; #define PROBE_BEGIN(id) unsigned long long pb_t0_##id = 0; if (PROBE_SEC == (id)) pb_t0_##id = __builtin_amdgcn_s_memrealtime();
; #define LAS __attribute__((address_space(3)))
; __device__ __forceinline__ void attn_compute(Frame& F, int id) {
;     const int b = id >> 5, n = (id >> 1) & 15, kvh = id & 1;
;     LAS unsigned char* lds = F.lds;
;     const bf16* Q = (const bf16*)(F.ws + WS_Q); const bf16* ZA = (const bf16*)(F.ws + WS_ZA);
;     bf16* A5 = (bf16*)(F.ws + WS_A5);
;     const float* sink = F.in[4];
;     const int lane = F.lane, wid = F.wave;
;     const int key0 = 128 * (n - 1);
;     PROBE_BEGIN(4)
;     const int g = wid >> 1, qh = wid & 1, h = kvh * 4 + g, r = lane & 31, hh = lane >> 5;
;     const float sk = sink[h] * LOG2E;
;     const size_t tok0 = (size_t)b * SEQ + 128 * n + 64 * qh + r;
;     bf16x8 qf[2][4];
; #pragma unroll
;     for (int qb = 0; qb < 2; ++qb)
; #pragma unroll
;         for (int st = 0; st < 4; ++st) qf[qb][st] = *(const bf16x8*)(Q + (tok0 + 32 * qb) * 512 + h * 64 + 16 * st + 8 * hh);
;     const LAS f32x4* BT4 = (const LAS f32x4*)(lds + OFF_B);
;     const int ktA = 2 * qh;
;     const LAS f32x4* BTg = BT4 + g * NBT + 63 - r + 4 * hh;
;     const LAS unsigned char* kbase = lds + OFF_K + (32 * ktA + r) * KROW + 16 * hh;
;     const LAS unsigned char* vbase = lds + OFF_V + r * VROW + (32 * ktA + 4 * hh) * 2;
;     float m0 = sk, m1 = sk, l0 = 0.f, l1 = 0.f;
;     f32x16 O0[2], O1[2];
; #pragma unroll
;     for (int q = 0; q < 16; ++q) { O0[0][q] = 0.f; O0[1][q] = 0.f; O1[0][q] = 0.f; O1[1][q] = 0.f; }
; #pragma unroll 1
;     for (int j = 0; j < 9; ++j) {
.LBB0_574:
	v_readfirstlane_b32 s4, v0
	s_nop 3
	s_bitcmp1_b32 s4, 8
	s_cbranch_scc0 .Lattn_lo_half
	s_setprio 1
	s_sleep 24
